# DMA issue of the next K tile interleaved behind the MFMAs of the current one (was a serial block between barrier and first fragment read)
# speedup vs baseline: 1.1084x; 1.0016x over previous
; template <int NI, bool DEEP = true>
; DEV void gemm_tile(f32x16 (&acc)[2][NI], const bf16* __restrict__ A, int lda, const bf16* __restrict__ Bt, int ldb,
;                    int K, bf16* sA, bf16* sB) {
;     ...
;   G_LOAD(ra0, rb0, 0)
;   if (DEEP) {
;     if (64 < K) G_LOAD(ra1, rb1, 64)
;     for (int k0 = 0; k0 < K; k0 += 128) {
;       G_STEP(ra0, rb0, k0 + 128)
;       if (k0 + 64 < K) G_STEP(ra1, rb1, k0 + 192)
;     }
.Lg1k_loop:
	s_waitcnt vmcnt(0)
	s_barrier
	ds_read_b128 v[88:91], v74 offset:0
	ds_read_b128 v[80:83], v70 offset:0
	ds_read_b128 v[84:87], v70 offset:4096
	ds_read_b128 v[92:95], v74 offset:4096
	s_waitcnt lgkmcnt(2)
	v_mfma_f32_32x32x16_bf16 v[52:67], v[88:91], v[80:83], v[52:67]
	s_add_u32 m0, s16, 0x8000
	s_nop 0
	global_load_lds_dwordx4 v68, s[98:99]
	ds_read_b128 v[104:107], v75 offset:0
	ds_read_b128 v[96:99], v71 offset:0
	s_waitcnt lgkmcnt(3)
	v_mfma_f32_32x32x16_bf16 v[20:35], v[88:91], v[84:87], v[20:35]
	s_add_u32 m0, s16, 0x8400
	s_add_u32 s14, s98, 0x4000
	s_addc_u32 s15, s99, 0
	global_load_lds_dwordx4 v69, s[14:15]
	ds_read_b128 v[100:103], v71 offset:4096
	s_waitcnt lgkmcnt(3)
	v_mfma_f32_32x32x16_bf16 v[36:51], v[92:95], v[80:83], v[36:51]
	s_add_u32 m0, s16, 0x8800
	s_add_u32 s14, s98, 0x8000
	s_addc_u32 s15, s99, 0
	global_load_lds_dwordx4 v68, s[14:15]
	ds_read_b128 v[108:111], v75 offset:4096
	v_mfma_f32_32x32x16_bf16 v[4:19], v[92:95], v[84:87], v[4:19]
	s_add_u32 m0, s16, 0x8c00
	s_add_u32 s14, s98, 0xc000
	s_addc_u32 s15, s99, 0
	global_load_lds_dwordx4 v69, s[14:15]
	s_waitcnt lgkmcnt(2)
	v_mfma_f32_32x32x16_bf16 v[52:67], v[104:107], v[96:99], v[52:67]
	s_add_u32 m0, s16, 0xd840
	s_nop 0
	global_load_lds_dwordx4 v68, s[100:101]
	ds_read_b128 v[88:91], v76 offset:0
	ds_read_b128 v[80:83], v72 offset:0
	s_waitcnt lgkmcnt(3)
	v_mfma_f32_32x32x16_bf16 v[20:35], v[104:107], v[100:103], v[20:35]
	s_add_u32 m0, s16, 0xdc40
	s_add_u32 s14, s100, 0x4000
	s_addc_u32 s15, s101, 0
	global_load_lds_dwordx4 v69, s[14:15]
	ds_read_b128 v[84:87], v72 offset:4096
	s_waitcnt lgkmcnt(3)
	v_mfma_f32_32x32x16_bf16 v[36:51], v[108:111], v[96:99], v[36:51]
	s_add_u32 m0, s16, 0xe040
	s_add_u32 s14, s100, 0x8000
	s_addc_u32 s15, s101, 0
	global_load_lds_dwordx4 v68, s[14:15]
	ds_read_b128 v[92:95], v76 offset:4096
	v_mfma_f32_32x32x16_bf16 v[4:19], v[108:111], v[100:103], v[4:19]
	s_add_u32 m0, s16, 0xe440
	s_add_u32 s14, s100, 0xc000
	s_addc_u32 s15, s101, 0
	global_load_lds_dwordx4 v69, s[14:15]
	s_waitcnt lgkmcnt(2)
	v_mfma_f32_32x32x16_bf16 v[52:67], v[88:91], v[80:83], v[52:67]
	s_add_u32 s98, s98, 0x80
	s_addc_u32 s99, s99, 0
	s_add_u32 s100, s100, 0x80
	s_addc_u32 s101, s101, 0
	ds_read_b128 v[104:107], v77 offset:0
	ds_read_b128 v[96:99], v73 offset:0
	s_waitcnt lgkmcnt(3)
	v_mfma_f32_32x32x16_bf16 v[20:35], v[88:91], v[84:87], v[20:35]
	ds_read_b128 v[100:103], v73 offset:4096
	s_waitcnt lgkmcnt(3)
	v_mfma_f32_32x32x16_bf16 v[36:51], v[92:95], v[80:83], v[36:51]
	ds_read_b128 v[108:111], v77 offset:4096
	v_mfma_f32_32x32x16_bf16 v[4:19], v[92:95], v[84:87], v[4:19]
	s_waitcnt lgkmcnt(2)
	v_mfma_f32_32x32x16_bf16 v[52:67], v[104:107], v[96:99], v[52:67]
	s_waitcnt lgkmcnt(1)
	v_mfma_f32_32x32x16_bf16 v[20:35], v[104:107], v[100:103], v[20:35]
	s_waitcnt lgkmcnt(0)
	v_mfma_f32_32x32x16_bf16 v[36:51], v[108:111], v[96:99], v[36:51]
	v_mfma_f32_32x32x16_bf16 v[4:19], v[108:111], v[100:103], v[4:19]
	s_waitcnt vmcnt(0)
	s_barrier
	s_cmp_eq_u32 s11, 7
	s_cbranch_scc1 .Lg1k_nodma
	ds_read_b128 v[88:91], v74 offset:38976
	ds_read_b128 v[80:83], v70 offset:32768
	ds_read_b128 v[84:87], v70 offset:36864
	ds_read_b128 v[92:95], v74 offset:43072
	s_waitcnt lgkmcnt(2)
	v_mfma_f32_32x32x16_bf16 v[52:67], v[88:91], v[80:83], v[52:67]
	s_add_u32 m0, s16, 0x0
	s_nop 0
	global_load_lds_dwordx4 v68, s[98:99]
	ds_read_b128 v[104:107], v75 offset:38976
	ds_read_b128 v[96:99], v71 offset:32768
	s_waitcnt lgkmcnt(3)
	v_mfma_f32_32x32x16_bf16 v[20:35], v[88:91], v[84:87], v[20:35]
	s_add_u32 m0, s16, 0x400
	s_add_u32 s14, s98, 0x4000
	s_addc_u32 s15, s99, 0
	global_load_lds_dwordx4 v69, s[14:15]
	ds_read_b128 v[100:103], v71 offset:36864
	s_waitcnt lgkmcnt(3)
	v_mfma_f32_32x32x16_bf16 v[36:51], v[92:95], v[80:83], v[36:51]
	s_add_u32 m0, s16, 0x800
	s_add_u32 s14, s98, 0x8000
	s_addc_u32 s15, s99, 0
	global_load_lds_dwordx4 v68, s[14:15]
	ds_read_b128 v[108:111], v75 offset:43072
	v_mfma_f32_32x32x16_bf16 v[4:19], v[92:95], v[84:87], v[4:19]
	s_add_u32 m0, s16, 0xc00
	s_add_u32 s14, s98, 0xc000
	s_addc_u32 s15, s99, 0
	global_load_lds_dwordx4 v69, s[14:15]
	s_waitcnt lgkmcnt(2)
	v_mfma_f32_32x32x16_bf16 v[52:67], v[104:107], v[96:99], v[52:67]
	s_add_u32 m0, s16, 0x4000
	s_nop 0
	global_load_lds_dwordx4 v68, s[100:101]
	ds_read_b128 v[88:91], v76 offset:38976
	ds_read_b128 v[80:83], v72 offset:32768
	s_waitcnt lgkmcnt(3)
	v_mfma_f32_32x32x16_bf16 v[20:35], v[104:107], v[100:103], v[20:35]
	s_add_u32 m0, s16, 0x4400
	s_add_u32 s14, s100, 0x4000
	s_addc_u32 s15, s101, 0
	global_load_lds_dwordx4 v69, s[14:15]
	ds_read_b128 v[84:87], v72 offset:36864
	s_waitcnt lgkmcnt(3)
	v_mfma_f32_32x32x16_bf16 v[36:51], v[108:111], v[96:99], v[36:51]
	s_add_u32 m0, s16, 0x4800
	s_add_u32 s14, s100, 0x8000
	s_addc_u32 s15, s101, 0
	global_load_lds_dwordx4 v68, s[14:15]
	ds_read_b128 v[92:95], v76 offset:43072
	v_mfma_f32_32x32x16_bf16 v[4:19], v[108:111], v[100:103], v[4:19]
	s_add_u32 m0, s16, 0x4c00
	s_add_u32 s14, s100, 0xc000
	s_addc_u32 s15, s101, 0
	global_load_lds_dwordx4 v69, s[14:15]
	s_waitcnt lgkmcnt(2)
	v_mfma_f32_32x32x16_bf16 v[52:67], v[88:91], v[80:83], v[52:67]
	s_add_u32 s98, s98, 0x80
	s_addc_u32 s99, s99, 0
	s_add_u32 s100, s100, 0x80
	s_addc_u32 s101, s101, 0
	ds_read_b128 v[104:107], v77 offset:38976
	ds_read_b128 v[96:99], v73 offset:32768
	s_waitcnt lgkmcnt(3)
	v_mfma_f32_32x32x16_bf16 v[20:35], v[88:91], v[84:87], v[20:35]
	ds_read_b128 v[100:103], v73 offset:36864
	s_waitcnt lgkmcnt(3)
	v_mfma_f32_32x32x16_bf16 v[36:51], v[92:95], v[80:83], v[36:51]
	ds_read_b128 v[108:111], v77 offset:43072
	v_mfma_f32_32x32x16_bf16 v[4:19], v[92:95], v[84:87], v[4:19]
	s_waitcnt lgkmcnt(2)
	v_mfma_f32_32x32x16_bf16 v[52:67], v[104:107], v[96:99], v[52:67]
	s_waitcnt lgkmcnt(1)
	v_mfma_f32_32x32x16_bf16 v[20:35], v[104:107], v[100:103], v[20:35]
	s_waitcnt lgkmcnt(0)
	v_mfma_f32_32x32x16_bf16 v[36:51], v[108:111], v[96:99], v[36:51]
	v_mfma_f32_32x32x16_bf16 v[4:19], v[108:111], v[100:103], v[4:19]
	s_branch .Lg1k_next

; template <int NI, bool DEEP = true>
; DEV void gemm_tile(f32x16 (&acc)[2][NI], const bf16* __restrict__ A, int lda, const bf16* __restrict__ Bt, int ldb,
;                    int K, bf16* sA, bf16* sB) {
;     ...
;     for (int k0 = 0; k0 < K; k0 += 128) {
;       G_STEP(ra0, rb0, k0 + 128)
;       if (k0 + 64 < K) G_STEP(ra1, rb1, k0 + 192)
;     }
.Lg1k_next:
	s_add_i32 s11, s11, 1
	s_cmp_lt_u32 s11, 8
	s_cbranch_scc1 .Lg1k_loop
	s_nop 7
	s_nop 7

; template <int NI, bool DEEP = true>
; DEV void gemm_tile(f32x16 (&acc)[2][NI], const bf16* __restrict__ A, int lda, const bf16* __restrict__ Bt, int ldb,
;                    int K, bf16* sA, bf16* sB) {
;     ...
;   G_LOAD(ra0, rb0, 0)
;   if (DEEP) {
;     if (64 < K) G_LOAD(ra1, rb1, 64)
;     for (int k0 = 0; k0 < K; k0 += 128) {
;       G_STEP(ra0, rb0, k0 + 128)
;       if (k0 + 64 < K) G_STEP(ra1, rb1, k0 + 192)
;     }
.Lgtk_loop:
	s_waitcnt vmcnt(0)
	s_barrier
	ds_read_b128 v[88:91], v74 offset:0
	ds_read_b128 v[80:83], v70 offset:0
	ds_read_b128 v[84:87], v70 offset:4096
	ds_read_b128 v[92:95], v74 offset:4096
	s_waitcnt lgkmcnt(2)
	v_mfma_f32_32x32x16_bf16 v[52:67], v[88:91], v[80:83], v[52:67]
	s_add_u32 m0, s0, 0x8000
	s_nop 0
	global_load_lds_dwordx4 v68, s[98:99]
	ds_read_b128 v[104:107], v75 offset:0
	ds_read_b128 v[96:99], v71 offset:0
	s_waitcnt lgkmcnt(3)
	v_mfma_f32_32x32x16_bf16 v[20:35], v[88:91], v[84:87], v[20:35]
	s_add_u32 m0, s0, 0x8400
	s_add_u32 s14, s98, 0x4000
	s_addc_u32 s15, s99, 0
	global_load_lds_dwordx4 v69, s[14:15]
	ds_read_b128 v[100:103], v71 offset:4096
	s_waitcnt lgkmcnt(3)
	v_mfma_f32_32x32x16_bf16 v[36:51], v[92:95], v[80:83], v[36:51]
	s_add_u32 m0, s0, 0x8800
	s_add_u32 s14, s98, 0x8000
	s_addc_u32 s15, s99, 0
	global_load_lds_dwordx4 v68, s[14:15]
	ds_read_b128 v[108:111], v75 offset:4096
	v_mfma_f32_32x32x16_bf16 v[4:19], v[92:95], v[84:87], v[4:19]
	s_add_u32 m0, s0, 0x8c00
	s_add_u32 s14, s98, 0xc000
	s_addc_u32 s15, s99, 0
	global_load_lds_dwordx4 v69, s[14:15]
	s_waitcnt lgkmcnt(2)
	v_mfma_f32_32x32x16_bf16 v[52:67], v[104:107], v[96:99], v[52:67]
	s_add_u32 m0, s0, 0xd840
	s_nop 0
	global_load_lds_dwordx4 v68, s[100:101]
	ds_read_b128 v[88:91], v76 offset:0
	ds_read_b128 v[80:83], v72 offset:0
	s_waitcnt lgkmcnt(3)
	v_mfma_f32_32x32x16_bf16 v[20:35], v[104:107], v[100:103], v[20:35]
	s_add_u32 m0, s0, 0xdc40
	s_add_u32 s14, s100, 0x4000
	s_addc_u32 s15, s101, 0
	global_load_lds_dwordx4 v69, s[14:15]
	ds_read_b128 v[84:87], v72 offset:4096
	s_waitcnt lgkmcnt(3)
	v_mfma_f32_32x32x16_bf16 v[36:51], v[108:111], v[96:99], v[36:51]
	s_add_u32 m0, s0, 0xe040
	s_add_u32 s14, s100, 0x8000
	s_addc_u32 s15, s101, 0
	global_load_lds_dwordx4 v68, s[14:15]
	ds_read_b128 v[92:95], v76 offset:4096
	v_mfma_f32_32x32x16_bf16 v[4:19], v[108:111], v[100:103], v[4:19]
	s_add_u32 m0, s0, 0xe440
	s_add_u32 s14, s100, 0xc000
	s_addc_u32 s15, s101, 0
	global_load_lds_dwordx4 v69, s[14:15]
	s_waitcnt lgkmcnt(2)
	v_mfma_f32_32x32x16_bf16 v[52:67], v[88:91], v[80:83], v[52:67]
	s_add_u32 s98, s98, 0x80
	s_addc_u32 s99, s99, 0
	s_add_u32 s100, s100, 0x80
	s_addc_u32 s101, s101, 0
	ds_read_b128 v[104:107], v77 offset:0
	ds_read_b128 v[96:99], v73 offset:0
	s_waitcnt lgkmcnt(3)
	v_mfma_f32_32x32x16_bf16 v[20:35], v[88:91], v[84:87], v[20:35]
	ds_read_b128 v[100:103], v73 offset:4096
	s_waitcnt lgkmcnt(3)
	v_mfma_f32_32x32x16_bf16 v[36:51], v[92:95], v[80:83], v[36:51]
	ds_read_b128 v[108:111], v77 offset:4096
	v_mfma_f32_32x32x16_bf16 v[4:19], v[92:95], v[84:87], v[4:19]
	s_waitcnt lgkmcnt(2)
	v_mfma_f32_32x32x16_bf16 v[52:67], v[104:107], v[96:99], v[52:67]
	s_waitcnt lgkmcnt(1)
	v_mfma_f32_32x32x16_bf16 v[20:35], v[104:107], v[100:103], v[20:35]
	s_waitcnt lgkmcnt(0)
	v_mfma_f32_32x32x16_bf16 v[36:51], v[108:111], v[96:99], v[36:51]
	v_mfma_f32_32x32x16_bf16 v[4:19], v[108:111], v[100:103], v[4:19]
	s_waitcnt vmcnt(0)
	s_barrier
	s_cmp_eq_u32 s11, 7
	s_cbranch_scc1 .Lgtk_nodma
	ds_read_b128 v[88:91], v74 offset:38976
	ds_read_b128 v[80:83], v70 offset:32768
	ds_read_b128 v[84:87], v70 offset:36864
	ds_read_b128 v[92:95], v74 offset:43072
	s_waitcnt lgkmcnt(2)
	v_mfma_f32_32x32x16_bf16 v[52:67], v[88:91], v[80:83], v[52:67]
	s_add_u32 m0, s0, 0x0
	s_nop 0
	global_load_lds_dwordx4 v68, s[98:99]
	ds_read_b128 v[104:107], v75 offset:38976
	ds_read_b128 v[96:99], v71 offset:32768
	s_waitcnt lgkmcnt(3)
	v_mfma_f32_32x32x16_bf16 v[20:35], v[88:91], v[84:87], v[20:35]
	s_add_u32 m0, s0, 0x400
	s_add_u32 s14, s98, 0x4000
	s_addc_u32 s15, s99, 0
	global_load_lds_dwordx4 v69, s[14:15]
	ds_read_b128 v[100:103], v71 offset:36864
	s_waitcnt lgkmcnt(3)
	v_mfma_f32_32x32x16_bf16 v[36:51], v[92:95], v[80:83], v[36:51]
	s_add_u32 m0, s0, 0x800
	s_add_u32 s14, s98, 0x8000
	s_addc_u32 s15, s99, 0
	global_load_lds_dwordx4 v68, s[14:15]
	ds_read_b128 v[108:111], v75 offset:43072
	v_mfma_f32_32x32x16_bf16 v[4:19], v[92:95], v[84:87], v[4:19]
	s_add_u32 m0, s0, 0xc00
	s_add_u32 s14, s98, 0xc000
	s_addc_u32 s15, s99, 0
	global_load_lds_dwordx4 v69, s[14:15]
	s_waitcnt lgkmcnt(2)
	v_mfma_f32_32x32x16_bf16 v[52:67], v[104:107], v[96:99], v[52:67]
	s_add_u32 m0, s0, 0x4000
	s_nop 0
	global_load_lds_dwordx4 v68, s[100:101]
	ds_read_b128 v[88:91], v76 offset:38976
	ds_read_b128 v[80:83], v72 offset:32768
	s_waitcnt lgkmcnt(3)
	v_mfma_f32_32x32x16_bf16 v[20:35], v[104:107], v[100:103], v[20:35]
	s_add_u32 m0, s0, 0x4400
	s_add_u32 s14, s100, 0x4000
	s_addc_u32 s15, s101, 0
	global_load_lds_dwordx4 v69, s[14:15]
	ds_read_b128 v[84:87], v72 offset:36864
	s_waitcnt lgkmcnt(3)
	v_mfma_f32_32x32x16_bf16 v[36:51], v[108:111], v[96:99], v[36:51]
	s_add_u32 m0, s0, 0x4800
	s_add_u32 s14, s100, 0x8000
	s_addc_u32 s15, s101, 0
	global_load_lds_dwordx4 v68, s[14:15]
	ds_read_b128 v[92:95], v76 offset:43072
	v_mfma_f32_32x32x16_bf16 v[4:19], v[108:111], v[100:103], v[4:19]
	s_add_u32 m0, s0, 0x4c00
	s_add_u32 s14, s100, 0xc000
	s_addc_u32 s15, s101, 0
	global_load_lds_dwordx4 v69, s[14:15]
	s_waitcnt lgkmcnt(2)
	v_mfma_f32_32x32x16_bf16 v[52:67], v[88:91], v[80:83], v[52:67]
	s_add_u32 s98, s98, 0x80
	s_addc_u32 s99, s99, 0
	s_add_u32 s100, s100, 0x80
	s_addc_u32 s101, s101, 0
	ds_read_b128 v[104:107], v77 offset:38976
	ds_read_b128 v[96:99], v73 offset:32768
	s_waitcnt lgkmcnt(3)
	v_mfma_f32_32x32x16_bf16 v[20:35], v[88:91], v[84:87], v[20:35]
	ds_read_b128 v[100:103], v73 offset:36864
	s_waitcnt lgkmcnt(3)
	v_mfma_f32_32x32x16_bf16 v[36:51], v[92:95], v[80:83], v[36:51]
	ds_read_b128 v[108:111], v77 offset:43072
	v_mfma_f32_32x32x16_bf16 v[4:19], v[92:95], v[84:87], v[4:19]
	s_waitcnt lgkmcnt(2)
	v_mfma_f32_32x32x16_bf16 v[52:67], v[104:107], v[96:99], v[52:67]
	s_waitcnt lgkmcnt(1)
	v_mfma_f32_32x32x16_bf16 v[20:35], v[104:107], v[100:103], v[20:35]
	s_waitcnt lgkmcnt(0)
	v_mfma_f32_32x32x16_bf16 v[36:51], v[108:111], v[96:99], v[36:51]
	v_mfma_f32_32x32x16_bf16 v[4:19], v[108:111], v[100:103], v[4:19]
	s_branch .Lgtk_next

; template <int NI, bool DEEP = true>
; DEV void gemm_tile(f32x16 (&acc)[2][NI], const bf16* __restrict__ A, int lda, const bf16* __restrict__ Bt, int ldb,
;                    int K, bf16* sA, bf16* sB) {
;     ...
;     for (int k0 = 0; k0 < K; k0 += 128) {
;       G_STEP(ra0, rb0, k0 + 128)
;       if (k0 + 64 < K) G_STEP(ra1, rb1, k0 + 192)
;     }
.Lgtk_next:
	s_add_i32 s11, s11, 1
	s_cmp_lt_u32 s11, 8
	s_cbranch_scc1 .Lgtk_loop
	s_nop 7
	s_nop 7
	s_branch .LBB0_867

; template <int NI, bool DEEP = true>
; DEV void gemm_tile(f32x16 (&acc)[2][NI], const bf16* __restrict__ A, int lda, const bf16* __restrict__ Bt, int ldb,
;                    int K, bf16* sA, bf16* sB) {
;     ...
;   G_LOAD(ra0, rb0, 0)
;   if (DEEP) {
;     if (64 < K) G_LOAD(ra1, rb1, 64)
;     for (int k0 = 0; k0 < K; k0 += 128) {
;       G_STEP(ra0, rb0, k0 + 128)
;       if (k0 + 64 < K) G_STEP(ra1, rb1, k0 + 192)
;     }
.Lmak_loop:
	s_waitcnt vmcnt(0)
	s_barrier
	ds_read_b128 v[40:43], v26 offset:0
	ds_read_b128 v[32:35], v22 offset:0
	ds_read_b128 v[36:39], v22 offset:4096
	ds_read_b128 v[44:47], v26 offset:4096
	s_waitcnt lgkmcnt(2)
	v_mfma_f32_32x32x16_bf16 v[116:131], v[40:43], v[32:35], v[116:131]
	s_add_u32 m0, s0, 0x8000
	s_nop 0
	global_load_lds_dwordx4 v20, s[98:99]
	ds_read_b128 v[56:59], v27 offset:0
	ds_read_b128 v[48:51], v23 offset:0
	s_waitcnt lgkmcnt(3)
	v_mfma_f32_32x32x16_bf16 v[68:83], v[40:43], v[36:39], v[68:83]
	s_add_u32 m0, s0, 0x8400
	s_add_u32 s34, s98, 0x4000
	s_addc_u32 s35, s99, 0
	global_load_lds_dwordx4 v21, s[34:35]
	ds_read_b128 v[52:55], v23 offset:4096
	s_waitcnt lgkmcnt(3)
	v_mfma_f32_32x32x16_bf16 v[100:115], v[44:47], v[32:35], v[100:115]
	s_add_u32 m0, s0, 0x8800
	s_add_u32 s34, s98, 0x8000
	s_addc_u32 s35, s99, 0
	global_load_lds_dwordx4 v20, s[34:35]
	ds_read_b128 v[60:63], v27 offset:4096
	v_mfma_f32_32x32x16_bf16 v[4:19], v[44:47], v[36:39], v[4:19]
	s_add_u32 m0, s0, 0x8c00
	s_add_u32 s34, s98, 0xc000
	s_addc_u32 s35, s99, 0
	global_load_lds_dwordx4 v21, s[34:35]
	s_waitcnt lgkmcnt(2)
	v_mfma_f32_32x32x16_bf16 v[116:131], v[56:59], v[48:51], v[116:131]
	s_add_u32 m0, s0, 0xd840
	s_nop 0
	global_load_lds_dwordx4 v20, s[100:101]
	ds_read_b128 v[40:43], v28 offset:0
	ds_read_b128 v[32:35], v24 offset:0
	s_waitcnt lgkmcnt(3)
	v_mfma_f32_32x32x16_bf16 v[68:83], v[56:59], v[52:55], v[68:83]
	s_add_u32 m0, s0, 0xdc40
	s_add_u32 s34, s100, 0x4000
	s_addc_u32 s35, s101, 0
	global_load_lds_dwordx4 v21, s[34:35]
	ds_read_b128 v[36:39], v24 offset:4096
	s_waitcnt lgkmcnt(3)
	v_mfma_f32_32x32x16_bf16 v[100:115], v[60:63], v[48:51], v[100:115]
	s_add_u32 m0, s0, 0xe040
	s_add_u32 s34, s100, 0x8000
	s_addc_u32 s35, s101, 0
	global_load_lds_dwordx4 v20, s[34:35]
	ds_read_b128 v[44:47], v28 offset:4096
	v_mfma_f32_32x32x16_bf16 v[4:19], v[60:63], v[52:55], v[4:19]
	s_add_u32 m0, s0, 0xe440
	s_add_u32 s34, s100, 0xc000
	s_addc_u32 s35, s101, 0
	global_load_lds_dwordx4 v21, s[34:35]
	s_waitcnt lgkmcnt(2)
	v_mfma_f32_32x32x16_bf16 v[116:131], v[40:43], v[32:35], v[116:131]
	s_add_u32 s98, s98, 0x80
	s_addc_u32 s99, s99, 0
	s_add_u32 s100, s100, 0x80
	s_addc_u32 s101, s101, 0
	ds_read_b128 v[56:59], v29 offset:0
	ds_read_b128 v[48:51], v25 offset:0
	s_waitcnt lgkmcnt(3)
	v_mfma_f32_32x32x16_bf16 v[68:83], v[40:43], v[36:39], v[68:83]
	ds_read_b128 v[52:55], v25 offset:4096
	s_waitcnt lgkmcnt(3)
	v_mfma_f32_32x32x16_bf16 v[100:115], v[44:47], v[32:35], v[100:115]
	ds_read_b128 v[60:63], v29 offset:4096
	v_mfma_f32_32x32x16_bf16 v[4:19], v[44:47], v[36:39], v[4:19]
	s_waitcnt lgkmcnt(2)
	v_mfma_f32_32x32x16_bf16 v[116:131], v[56:59], v[48:51], v[116:131]
	s_waitcnt lgkmcnt(1)
	v_mfma_f32_32x32x16_bf16 v[68:83], v[56:59], v[52:55], v[68:83]
	s_waitcnt lgkmcnt(0)
	v_mfma_f32_32x32x16_bf16 v[100:115], v[60:63], v[48:51], v[100:115]
	v_mfma_f32_32x32x16_bf16 v[4:19], v[60:63], v[52:55], v[4:19]
	s_waitcnt vmcnt(0)
	s_barrier
	s_cmp_eq_u32 s28, 7
	s_cbranch_scc1 .Lmak_nodma
	ds_read_b128 v[40:43], v26 offset:38976
	ds_read_b128 v[32:35], v22 offset:32768
	ds_read_b128 v[36:39], v22 offset:36864
	ds_read_b128 v[44:47], v26 offset:43072
	s_waitcnt lgkmcnt(2)
	v_mfma_f32_32x32x16_bf16 v[116:131], v[40:43], v[32:35], v[116:131]
	s_add_u32 m0, s0, 0x0
	s_nop 0
	global_load_lds_dwordx4 v20, s[98:99]
	ds_read_b128 v[56:59], v27 offset:38976
	ds_read_b128 v[48:51], v23 offset:32768
	s_waitcnt lgkmcnt(3)
	v_mfma_f32_32x32x16_bf16 v[68:83], v[40:43], v[36:39], v[68:83]
	s_add_u32 m0, s0, 0x400
	s_add_u32 s34, s98, 0x4000
	s_addc_u32 s35, s99, 0
	global_load_lds_dwordx4 v21, s[34:35]
	ds_read_b128 v[52:55], v23 offset:36864
	s_waitcnt lgkmcnt(3)
	v_mfma_f32_32x32x16_bf16 v[100:115], v[44:47], v[32:35], v[100:115]
	s_add_u32 m0, s0, 0x800
	s_add_u32 s34, s98, 0x8000
	s_addc_u32 s35, s99, 0
	global_load_lds_dwordx4 v20, s[34:35]
	ds_read_b128 v[60:63], v27 offset:43072
	v_mfma_f32_32x32x16_bf16 v[4:19], v[44:47], v[36:39], v[4:19]
	s_add_u32 m0, s0, 0xc00
	s_add_u32 s34, s98, 0xc000
	s_addc_u32 s35, s99, 0
	global_load_lds_dwordx4 v21, s[34:35]
	s_waitcnt lgkmcnt(2)
	v_mfma_f32_32x32x16_bf16 v[116:131], v[56:59], v[48:51], v[116:131]
	s_add_u32 m0, s0, 0x4000
	s_nop 0
	global_load_lds_dwordx4 v20, s[100:101]
	ds_read_b128 v[40:43], v28 offset:38976
	ds_read_b128 v[32:35], v24 offset:32768
	s_waitcnt lgkmcnt(3)
	v_mfma_f32_32x32x16_bf16 v[68:83], v[56:59], v[52:55], v[68:83]
	s_add_u32 m0, s0, 0x4400
	s_add_u32 s34, s100, 0x4000
	s_addc_u32 s35, s101, 0
	global_load_lds_dwordx4 v21, s[34:35]
	ds_read_b128 v[36:39], v24 offset:36864
	s_waitcnt lgkmcnt(3)
	v_mfma_f32_32x32x16_bf16 v[100:115], v[60:63], v[48:51], v[100:115]
	s_add_u32 m0, s0, 0x4800
	s_add_u32 s34, s100, 0x8000
	s_addc_u32 s35, s101, 0
	global_load_lds_dwordx4 v20, s[34:35]
	ds_read_b128 v[44:47], v28 offset:43072
	v_mfma_f32_32x32x16_bf16 v[4:19], v[60:63], v[52:55], v[4:19]
	s_add_u32 m0, s0, 0x4c00
	s_add_u32 s34, s100, 0xc000
	s_addc_u32 s35, s101, 0
	global_load_lds_dwordx4 v21, s[34:35]
	s_waitcnt lgkmcnt(2)
	v_mfma_f32_32x32x16_bf16 v[116:131], v[40:43], v[32:35], v[116:131]
	s_add_u32 s98, s98, 0x80
	s_addc_u32 s99, s99, 0
	s_add_u32 s100, s100, 0x80
	s_addc_u32 s101, s101, 0
	ds_read_b128 v[56:59], v29 offset:38976
	ds_read_b128 v[48:51], v25 offset:32768
	s_waitcnt lgkmcnt(3)
	v_mfma_f32_32x32x16_bf16 v[68:83], v[40:43], v[36:39], v[68:83]
	ds_read_b128 v[52:55], v25 offset:36864
	s_waitcnt lgkmcnt(3)
	v_mfma_f32_32x32x16_bf16 v[100:115], v[44:47], v[32:35], v[100:115]
	ds_read_b128 v[60:63], v29 offset:43072
	v_mfma_f32_32x32x16_bf16 v[4:19], v[44:47], v[36:39], v[4:19]
	s_waitcnt lgkmcnt(2)
	v_mfma_f32_32x32x16_bf16 v[116:131], v[56:59], v[48:51], v[116:131]
	s_waitcnt lgkmcnt(1)
	v_mfma_f32_32x32x16_bf16 v[68:83], v[56:59], v[52:55], v[68:83]
	s_waitcnt lgkmcnt(0)
	v_mfma_f32_32x32x16_bf16 v[100:115], v[60:63], v[48:51], v[100:115]
	v_mfma_f32_32x32x16_bf16 v[4:19], v[60:63], v[52:55], v[4:19]
	s_branch .Lmak_next

; template <int NI, bool DEEP = true>
; DEV void gemm_tile(f32x16 (&acc)[2][NI], const bf16* __restrict__ A, int lda, const bf16* __restrict__ Bt, int ldb,
;                    int K, bf16* sA, bf16* sB) {
;     ...
;     for (int k0 = 0; k0 < K; k0 += 128) {
;       G_STEP(ra0, rb0, k0 + 128)
;       if (k0 + 64 < K) G_STEP(ra1, rb1, k0 + 192)
;     }
.Lmak_next:
	s_add_i32 s28, s28, 1
	s_cmp_lt_u32 s28, 8
	s_cbranch_scc1 .Lmak_loop
	s_nop 7
	s_nop 7

; template <int NI, bool DEEP = true>
; DEV void gemm_tile(f32x16 (&acc)[2][NI], const bf16* __restrict__ A, int lda, const bf16* __restrict__ Bt, int ldb,
;                    int K, bf16* sA, bf16* sB) {
;     ...
;   G_LOAD(ra0, rb0, 0)
;   if (DEEP) {
;     if (64 < K) G_LOAD(ra1, rb1, 64)
;     for (int k0 = 0; k0 < K; k0 += 128) {
;       G_STEP(ra0, rb0, k0 + 128)
;       if (k0 + 64 < K) G_STEP(ra1, rb1, k0 + 192)
;     }
.Lotk_loop:
	s_waitcnt vmcnt(0)
	s_barrier
	ds_read_b128 v[88:91], v74 offset:0
	ds_read_b128 v[80:83], v70 offset:0
	ds_read_b128 v[84:87], v70 offset:4096
	ds_read_b128 v[92:95], v74 offset:4096
	s_waitcnt lgkmcnt(2)
	v_mfma_f32_32x32x16_bf16 v[52:67], v[88:91], v[80:83], v[52:67]
	s_add_u32 m0, s16, 0x8000
	s_nop 0
	global_load_lds_dwordx4 v68, s[98:99]
	ds_read_b128 v[104:107], v75 offset:0
	ds_read_b128 v[96:99], v71 offset:0
	s_waitcnt lgkmcnt(3)
	v_mfma_f32_32x32x16_bf16 v[20:35], v[88:91], v[84:87], v[20:35]
	s_add_u32 m0, s16, 0x8400
	s_add_u32 s14, s98, 0x4000
	s_addc_u32 s15, s99, 0
	global_load_lds_dwordx4 v69, s[14:15]
	ds_read_b128 v[100:103], v71 offset:4096
	s_waitcnt lgkmcnt(3)
	v_mfma_f32_32x32x16_bf16 v[36:51], v[92:95], v[80:83], v[36:51]
	s_add_u32 m0, s16, 0x8800
	s_add_u32 s14, s98, 0x8000
	s_addc_u32 s15, s99, 0
	global_load_lds_dwordx4 v68, s[14:15]
	ds_read_b128 v[108:111], v75 offset:4096
	v_mfma_f32_32x32x16_bf16 v[4:19], v[92:95], v[84:87], v[4:19]
	s_add_u32 m0, s16, 0x8c00
	s_add_u32 s14, s98, 0xc000
	s_addc_u32 s15, s99, 0
	global_load_lds_dwordx4 v69, s[14:15]
	s_waitcnt lgkmcnt(2)
	v_mfma_f32_32x32x16_bf16 v[52:67], v[104:107], v[96:99], v[52:67]
	s_add_u32 m0, s16, 0xd840
	s_nop 0
	global_load_lds_dwordx4 v68, s[100:101]
	ds_read_b128 v[88:91], v76 offset:0
	ds_read_b128 v[80:83], v72 offset:0
	s_waitcnt lgkmcnt(3)
	v_mfma_f32_32x32x16_bf16 v[20:35], v[104:107], v[100:103], v[20:35]
	s_add_u32 m0, s16, 0xdc40
	s_add_u32 s14, s100, 0x4000
	s_addc_u32 s15, s101, 0
	global_load_lds_dwordx4 v69, s[14:15]
	ds_read_b128 v[84:87], v72 offset:4096
	s_waitcnt lgkmcnt(3)
	v_mfma_f32_32x32x16_bf16 v[36:51], v[108:111], v[96:99], v[36:51]
	s_add_u32 m0, s16, 0xe040
	s_add_u32 s14, s100, 0x8000
	s_addc_u32 s15, s101, 0
	global_load_lds_dwordx4 v68, s[14:15]
	ds_read_b128 v[92:95], v76 offset:4096
	v_mfma_f32_32x32x16_bf16 v[4:19], v[108:111], v[100:103], v[4:19]
	s_add_u32 m0, s16, 0xe440
	s_add_u32 s14, s100, 0xc000
	s_addc_u32 s15, s101, 0
	global_load_lds_dwordx4 v69, s[14:15]
	s_waitcnt lgkmcnt(2)
	v_mfma_f32_32x32x16_bf16 v[52:67], v[88:91], v[80:83], v[52:67]
	s_add_u32 s98, s98, 0x80
	s_addc_u32 s99, s99, 0
	s_add_u32 s100, s100, 0x80
	s_addc_u32 s101, s101, 0
	ds_read_b128 v[104:107], v77 offset:0
	ds_read_b128 v[96:99], v73 offset:0
	s_waitcnt lgkmcnt(3)
	v_mfma_f32_32x32x16_bf16 v[20:35], v[88:91], v[84:87], v[20:35]
	ds_read_b128 v[100:103], v73 offset:4096
	s_waitcnt lgkmcnt(3)
	v_mfma_f32_32x32x16_bf16 v[36:51], v[92:95], v[80:83], v[36:51]
	ds_read_b128 v[108:111], v77 offset:4096
	v_mfma_f32_32x32x16_bf16 v[4:19], v[92:95], v[84:87], v[4:19]
	s_waitcnt lgkmcnt(2)
	v_mfma_f32_32x32x16_bf16 v[52:67], v[104:107], v[96:99], v[52:67]
	s_waitcnt lgkmcnt(1)
	v_mfma_f32_32x32x16_bf16 v[20:35], v[104:107], v[100:103], v[20:35]
	s_waitcnt lgkmcnt(0)
	v_mfma_f32_32x32x16_bf16 v[36:51], v[108:111], v[96:99], v[36:51]
	v_mfma_f32_32x32x16_bf16 v[4:19], v[108:111], v[100:103], v[4:19]
	s_waitcnt vmcnt(0)
	s_barrier
	s_cmp_eq_u32 s5, 7
	s_cbranch_scc1 .Lotk_nodma
	ds_read_b128 v[88:91], v74 offset:38976
	ds_read_b128 v[80:83], v70 offset:32768
	ds_read_b128 v[84:87], v70 offset:36864
	ds_read_b128 v[92:95], v74 offset:43072
	s_waitcnt lgkmcnt(2)
	v_mfma_f32_32x32x16_bf16 v[52:67], v[88:91], v[80:83], v[52:67]
	s_add_u32 m0, s16, 0x0
	s_nop 0
	global_load_lds_dwordx4 v68, s[98:99]
	ds_read_b128 v[104:107], v75 offset:38976
	ds_read_b128 v[96:99], v71 offset:32768
	s_waitcnt lgkmcnt(3)
	v_mfma_f32_32x32x16_bf16 v[20:35], v[88:91], v[84:87], v[20:35]
	s_add_u32 m0, s16, 0x400
	s_add_u32 s14, s98, 0x4000
	s_addc_u32 s15, s99, 0
	global_load_lds_dwordx4 v69, s[14:15]
	ds_read_b128 v[100:103], v71 offset:36864
	s_waitcnt lgkmcnt(3)
	v_mfma_f32_32x32x16_bf16 v[36:51], v[92:95], v[80:83], v[36:51]
	s_add_u32 m0, s16, 0x800
	s_add_u32 s14, s98, 0x8000
	s_addc_u32 s15, s99, 0
	global_load_lds_dwordx4 v68, s[14:15]
	ds_read_b128 v[108:111], v75 offset:43072
	v_mfma_f32_32x32x16_bf16 v[4:19], v[92:95], v[84:87], v[4:19]
	s_add_u32 m0, s16, 0xc00
	s_add_u32 s14, s98, 0xc000
	s_addc_u32 s15, s99, 0
	global_load_lds_dwordx4 v69, s[14:15]
	s_waitcnt lgkmcnt(2)
	v_mfma_f32_32x32x16_bf16 v[52:67], v[104:107], v[96:99], v[52:67]
	s_add_u32 m0, s16, 0x4000
	s_nop 0
	global_load_lds_dwordx4 v68, s[100:101]
	ds_read_b128 v[88:91], v76 offset:38976
	ds_read_b128 v[80:83], v72 offset:32768
	s_waitcnt lgkmcnt(3)
	v_mfma_f32_32x32x16_bf16 v[20:35], v[104:107], v[100:103], v[20:35]
	s_add_u32 m0, s16, 0x4400
	s_add_u32 s14, s100, 0x4000
	s_addc_u32 s15, s101, 0
	global_load_lds_dwordx4 v69, s[14:15]
	ds_read_b128 v[84:87], v72 offset:36864
	s_waitcnt lgkmcnt(3)
	v_mfma_f32_32x32x16_bf16 v[36:51], v[108:111], v[96:99], v[36:51]
	s_add_u32 m0, s16, 0x4800
	s_add_u32 s14, s100, 0x8000
	s_addc_u32 s15, s101, 0
	global_load_lds_dwordx4 v68, s[14:15]
	ds_read_b128 v[92:95], v76 offset:43072
	v_mfma_f32_32x32x16_bf16 v[4:19], v[108:111], v[100:103], v[4:19]
	s_add_u32 m0, s16, 0x4c00
	s_add_u32 s14, s100, 0xc000
	s_addc_u32 s15, s101, 0
	global_load_lds_dwordx4 v69, s[14:15]
	s_waitcnt lgkmcnt(2)
	v_mfma_f32_32x32x16_bf16 v[52:67], v[88:91], v[80:83], v[52:67]
	s_add_u32 s98, s98, 0x80
	s_addc_u32 s99, s99, 0
	s_add_u32 s100, s100, 0x80
	s_addc_u32 s101, s101, 0
	ds_read_b128 v[104:107], v77 offset:38976
	ds_read_b128 v[96:99], v73 offset:32768
	s_waitcnt lgkmcnt(3)
	v_mfma_f32_32x32x16_bf16 v[20:35], v[88:91], v[84:87], v[20:35]
	ds_read_b128 v[100:103], v73 offset:36864
	s_waitcnt lgkmcnt(3)
	v_mfma_f32_32x32x16_bf16 v[36:51], v[92:95], v[80:83], v[36:51]
	ds_read_b128 v[108:111], v77 offset:43072
	v_mfma_f32_32x32x16_bf16 v[4:19], v[92:95], v[84:87], v[4:19]
	s_waitcnt lgkmcnt(2)
	v_mfma_f32_32x32x16_bf16 v[52:67], v[104:107], v[96:99], v[52:67]
	s_waitcnt lgkmcnt(1)
	v_mfma_f32_32x32x16_bf16 v[20:35], v[104:107], v[100:103], v[20:35]
	s_waitcnt lgkmcnt(0)
	v_mfma_f32_32x32x16_bf16 v[36:51], v[108:111], v[96:99], v[36:51]
	v_mfma_f32_32x32x16_bf16 v[4:19], v[108:111], v[100:103], v[4:19]
	s_branch .Lotk_next

; template <int NI, bool DEEP = true>
; DEV void gemm_tile(f32x16 (&acc)[2][NI], const bf16* __restrict__ A, int lda, const bf16* __restrict__ Bt, int ldb,
;                    int K, bf16* sA, bf16* sB) {
;     ...
;     for (int k0 = 0; k0 < K; k0 += 128) {
;       G_STEP(ra0, rb0, k0 + 128)
;       if (k0 + 64 < K) G_STEP(ra1, rb1, k0 + 192)
;     }
.Lotk_next:
	s_add_i32 s5, s5, 1
	s_cmp_lt_u32 s5, 8
	s_cbranch_scc1 .Lotk_loop
	s_nop 7
	s_nop 7
